# P2 tile order: unit 1 exchanges column tile with XCD-pair partner (pn +-10) so each WG mixes q/k (heavy epilogue) and v/g (light) tiles
# speedup vs baseline: 1.0096x; 1.0096x over previous
.LBB0_166:
	v_readlane_b32 s6, v255, 20
	v_readlane_b32 s7, v255, 21
	s_load_dword s7, s[6:7], 0xe0
	s_add_i32 s48, s48, 1
	s_mul_i32 s3, s48, s94
	s_waitcnt lgkmcnt(0)
	s_mul_hi_u32 s6, s48, s7
	s_add_i32 s6, s6, s3
	s_mul_i32 s3, s48, s7
	s_add_u32 s86, s3, s92
	s_addc_u32 s87, s6, s95
	v_cmp_gt_i64_e32 vcc, s[86:87], v[152:153]
	v_cmp_lt_i64_e64 s[6:7], s[86:87], v[150:151]
	s_cbranch_vccnz .LBB0_168
	s_ashr_i32 s3, s86, 31
	s_lshr_b32 s3, s3, 29
	s_add_i32 s3, s86, s3
	s_ashr_i32 s21, s3, 3
	s_and_b32 s3, s3, -8
	s_sub_i32 s3, s86, s3
	s_cmp_lt_i32 s3, 0
	s_movk_i32 s35, 0x51
	s_cselect_b32 s35, s35, 0x50
	s_mul_i32 s3, s3, s35
	s_add_i32 s3, s3, s21
	s_mul_hi_i32 s21, s3, 0x66666667
	s_lshr_b32 s35, s21, 31
	s_ashr_i32 s21, s21, 6
	s_add_i32 s21, s21, s35
	s_lshl_b32 s35, s21, 3
	s_sub_i32 s40, 32, s35
	s_min_i32 s40, s40, 8
	s_abs_i32 s49, s40
	v_cvt_f32_u32_e32 v2, s49
	s_sub_i32 s76, 0, s49
	s_mulk_i32 s21, 0xa0
	s_sub_i32 s3, s3, s21
	v_rcp_iflag_f32_e32 v2, v2
	s_abs_i32 s21, s3
	s_xor_b32 s50, s3, s40
	s_ashr_i32 s50, s50, 31
	v_mul_f32_e32 v2, 0x4f7ffffe, v2
	v_cvt_u32_f32_e32 v2, v2
	s_nop 0
	v_readfirstlane_b32 s77, v2
	s_mul_i32 s76, s76, s77
	s_mul_hi_u32 s76, s77, s76
	s_add_i32 s77, s77, s76
	s_mul_hi_u32 s76, s21, s77
	s_mul_i32 s77, s76, s49
	s_sub_i32 s21, s21, s77
	s_add_i32 s78, s76, 1
	s_sub_i32 s77, s21, s49
	s_cmp_ge_u32 s21, s49
	s_cselect_b32 s76, s78, s76
	s_cselect_b32 s21, s77, s21
	s_add_i32 s77, s76, 1
	s_cmp_ge_u32 s21, s49
	s_cselect_b32 s21, s77, s76
	s_xor_b32 s21, s21, s50
	s_sub_i32 s49, s21, s50
	s_mul_i32 s21, s49, s40
	s_sub_i32 s3, s3, s21
	s_add_i32 s35, s35, s3
	s_cmp_lg_u32 s48, 1
	s_cbranch_scc1 .Lp2_noswap
	s_cmp_lt_i32 s49, 10
	s_cselect_b32 s3, 10, -10
	s_add_i32 s49, s49, s3
.Lp2_noswap:
	s_lshl_b32 s76, s35, 1
	s_ashr_i32 s77, s76, 31
	s_lshl_b64 s[76:77], s[76:77], 19
	s_add_u32 s76, s62, s76
	s_addc_u32 s77, s63, s77
	s_add_u32 s78, s76, 0x80000
	s_addc_u32 s79, s77, 0
	s_lshl_b32 s80, s49, 1
	s_ashr_i32 s81, s80, 31
	s_lshl_b64 s[80:81], s[80:81], 19
	s_add_u32 s80, s36, s80
	s_addc_u32 s81, s37, s81
	s_add_u32 s82, s80, 0x80000
	s_addc_u32 s83, s81, 0
